# in-proj q/k epilogue: 8 rope cos/sin loads batched up front with counted vmcnt (were 4 serialized load-wait-math rounds), 2 late norm-weight loads hoisted
# baseline (speedup 1.0000x reference)
; DI int crow(int reg, int h) { return (reg & 3) + 8 * (reg >> 2) + 4 * h; }
; DI void phase_in(const Params& p, char* wsb, int layer, char* lds) {
;     ...
;         const float* gain = (na ? (kind == 0 ? p.na_qg : p.na_kg) : (kind == 0 ? p.swa_qg : p.swa_kg)) + layer * 64;
;         float ss = 0.f;
; #pragma unroll
;         for (int ai = 0; ai < 2; ++ai)
; #pragma unroll
;           for (int reg = 0; reg < 16; ++reg) ss += acc[ai][bi][reg] * acc[ai][bi][reg];
;         ss += __shfl_xor(ss, 32);
;         const float rn = rsqrtf(ss * (1.f / 64.f) + 1e-6f);
;         float v[2][16];
; #pragma unroll
;         for (int ai = 0; ai < 2; ++ai)
; #pragma unroll
;           for (int reg = 0; reg < 16; ++reg) v[ai][reg] = acc[ai][bi][reg] * rn * gain[ai * 32 + crow(reg, h)];
.LBB0_612:
	s_xor_b64 s[54:55], s[8:9], -1
	v_cmp_eq_u32_e64 s[8:9], 0, v0
	v_cmp_ne_u32_e64 s[10:11], 2, v0
	s_or_b64 s[56:57], s[6:7], s[8:9]
	v_cndmask_b32_e64 v0, v196, v197, s[8:9]
	v_cndmask_b32_e64 v78, v198, v199, s[8:9]
	v_cndmask_b32_e64 v0, v78, v0, s[6:7]
	v_cndmask_b32_e64 v121, 1.0, v195, s[8:9]
	v_lshl_add_u64 v[78:79], s[14:15], 0, v[0:1]
	v_cndmask_b32_e64 v122, 1, 3, s[56:57]
	s_and_saveexec_b64 s[56:57], s[10:11]
	s_xor_b64 s[56:57], exec, s[56:57]
	s_cbranch_execz .LBB0_616
	v_cndmask_b32_e64 v0, v200, v201, s[8:9]
	v_cndmask_b32_e64 v84, v202, v203, s[8:9]
	v_readlane_b32 s58, v244, 0
	v_cndmask_b32_e64 v0, v84, v0, s[6:7]
	v_readlane_b32 s59, v244, 1
	v_pk_mul_f32 v[94:95], v[40:41], v[40:41]
	v_pk_mul_f32 v[92:93], v[42:43], v[42:43]
	v_lshl_add_u64 v[84:85], s[58:59], 0, v[0:1]
	global_load_dwordx2 v[84:85], v[84:85], off
	v_mul_f32_e32 v0, v51, v51
	v_fmac_f32_e32 v0, v50, v50
	v_fmac_f32_e32 v0, v52, v52
	v_fmac_f32_e32 v0, v53, v53
	v_fmac_f32_e32 v0, v54, v54
	v_fmac_f32_e32 v0, v55, v55
	v_fmac_f32_e32 v0, v56, v56
	v_fmac_f32_e32 v0, v57, v57
	v_fmac_f32_e32 v0, v58, v58
	v_fmac_f32_e32 v0, v59, v59
	v_fmac_f32_e32 v0, v60, v60
	v_fmac_f32_e32 v0, v61, v61
	v_fmac_f32_e32 v0, v62, v62
	v_fmac_f32_e32 v0, v63, v63
	v_fmac_f32_e32 v0, v64, v64
	v_fmac_f32_e32 v0, v65, v65
	v_fmac_f32_e32 v0, v34, v34
	v_fmac_f32_e32 v0, v35, v35
	v_fmac_f32_e32 v0, v36, v36
	v_fmac_f32_e32 v0, v37, v37
	v_fmac_f32_e32 v0, v38, v38
	v_fmac_f32_e32 v0, v39, v39
	v_add_f32_e32 v0, v94, v0
	v_add_f32_e32 v0, v95, v0
	v_add_f32_e32 v0, v92, v0
	v_pk_mul_f32 v[90:91], v[44:45], v[44:45]
	v_add_f32_e32 v0, v93, v0
	v_add_f32_e32 v0, v90, v0
	v_pk_mul_f32 v[88:89], v[46:47], v[46:47]
	v_add_f32_e32 v0, v91, v0
	v_add_f32_e32 v0, v88, v0
	v_pk_mul_f32 v[86:87], v[48:49], v[48:49]
	v_add_f32_e32 v0, v89, v0
	v_cmp_lt_i32_e32 vcc, v187, v186
	v_add_f32_e32 v0, v86, v0
	v_add_f32_e32 v0, v87, v0
	v_cndmask_b32_e32 v86, v185, v187, vcc
	v_lshlrev_b32_e32 v86, 2, v86
	ds_bpermute_b32 v86, v86, v0
	s_waitcnt lgkmcnt(0)
	v_add_f32_e32 v0, v0, v86
	v_fmamk_f32 v0, v0, 0x3c800000, v179
	v_cmp_gt_f32_e32 vcc, s66, v0
	v_mul_f32_e32 v86, 0x4b800000, v0
	s_waitcnt vmcnt(0)
	v_lshl_add_u64 v[84:85], s[18:19], 2, v[84:85]
	v_cndmask_b32_e32 v0, v0, v86, vcc
	v_rsq_f32_e32 v0, v0
	s_nop 0
	v_mul_f32_e32 v86, 0x45800000, v0
	v_cndmask_b32_e32 v112, v0, v86, vcc
	v_lshlrev_b32_e32 v0, 2, v66
	v_lshl_add_u64 v[114:115], v[84:85], 0, v[0:1]
	global_load_dwordx4 v[84:87], v[114:115], off
	global_load_dwordx4 v[90:93], v[114:115], off offset:64
	global_load_dwordx4 v[246:249], v[114:115], off offset:32
	global_load_dwordx4 v[250:253], v[114:115], off offset:128
	v_pk_mul_f32 v[88:89], v[50:51], v[112:113] op_sel_hi:[1,0]
	v_pk_mul_f32 v[96:97], v[54:55], v[112:113] op_sel_hi:[1,0]
	global_load_dwordx4 v[106:109], v[114:115], off offset:192
	global_load_dwordx4 v[134:137], v[114:115], off offset:224
	v_pk_mul_f32 v[104:105], v[34:35], v[112:113] op_sel_hi:[1,0]
	global_load_dwordx4 v[98:101], v[114:115], off offset:96
	global_load_dwordx4 v[126:129], v[114:115], off offset:160
	s_waitcnt vmcnt(5)
	v_pk_mul_f32 v[88:89], v[84:85], v[88:89]
	v_pk_mul_f32 v[84:85], v[58:59], v[112:113] op_sel_hi:[1,0]
	s_waitcnt vmcnt(4)
	v_pk_mul_f32 v[84:85], v[90:91], v[84:85]
	v_pk_mul_f32 v[90:91], v[52:53], v[112:113] op_sel_hi:[1,0]
	s_nop 0
	v_pk_mul_f32 v[90:91], v[86:87], v[90:91]
	v_pk_mul_f32 v[86:87], v[60:61], v[112:113] op_sel_hi:[1,0]
	s_nop 0
	v_pk_mul_f32 v[86:87], v[86:87], v[92:93]
	s_waitcnt vmcnt(0)
	v_pk_mul_f32 v[96:97], v[246:247], v[96:97]
	v_pk_mul_f32 v[92:93], v[62:63], v[112:113] op_sel_hi:[1,0]
	s_nop 0
	v_pk_mul_f32 v[92:93], v[92:93], v[98:99]
	v_pk_mul_f32 v[98:99], v[56:57], v[112:113] op_sel_hi:[1,0]
	s_nop 0
	v_pk_mul_f32 v[98:99], v[248:249], v[98:99]
	v_pk_mul_f32 v[94:95], v[64:65], v[112:113] op_sel_hi:[1,0]
	s_nop 0
	v_pk_mul_f32 v[94:95], v[94:95], v[100:101]
	v_pk_mul_f32 v[114:115], v[40:41], v[112:113] op_sel_hi:[1,0]
	s_waitcnt vmcnt(0)
	v_pk_mul_f32 v[104:105], v[104:105], v[250:251]
	v_pk_mul_f32 v[100:101], v[42:43], v[112:113] op_sel_hi:[1,0]
	v_pk_mul_f32 v[114:115], v[114:115], v[128:129]
	v_pk_mul_f32 v[100:101], v[100:101], v[106:107]
	v_pk_mul_f32 v[106:107], v[36:37], v[112:113] op_sel_hi:[1,0]
	s_nop 0
	v_pk_mul_f32 v[106:107], v[106:107], v[252:253]
	v_pk_mul_f32 v[102:103], v[44:45], v[112:113] op_sel_hi:[1,0]
	s_nop 0
	v_pk_mul_f32 v[102:103], v[102:103], v[108:109]
	v_pk_mul_f32 v[108:109], v[38:39], v[112:113] op_sel_hi:[1,0]
	s_nop 0
	v_pk_mul_f32 v[110:111], v[108:109], v[126:127]
	v_pk_mul_f32 v[108:109], v[46:47], v[112:113] op_sel_hi:[1,0]
	v_pk_mul_f32 v[112:113], v[48:49], v[112:113] op_sel_hi:[1,0]
	v_pk_mul_f32 v[108:109], v[108:109], v[134:135]
	v_pk_mul_f32 v[112:113], v[112:113], v[136:137]
	s_and_saveexec_b64 s[58:59], s[54:55]
	s_cbranch_execz .LBB0_615
; DI int crow(int reg, int h) { return (reg & 3) + 8 * (reg >> 2) + 4 * h; }
; DI void phase_in(const Params& p, char* wsb, int layer, char* lds) {
;     ...
;         if (!na && !isctx) {
;           const int prow = pos >> 6, pcol = pos & 63;
; #pragma unroll
;           for (int ai = 0; ai < 2; ++ai) {
;             const float* ct = ai == 0 ? rope + prow * 16 : rope + 1024 + pcol * 16;
;             const float* st = ai == 0 ? rope + 512 + prow * 16 : rope + 2048 + pcol * 16;
; #pragma unroll
;             for (int reg = 0; reg < 8; ++reg) {
;               int j = crow(reg, h);
;               float cs = ct[j], sn = st[j];
;               float x1 = v[ai][reg], x2 = v[ai][reg + 8];
;               v[ai][reg] = x1 * cs - x2 * sn;
;               v[ai][reg + 8] = x2 * cs + x1 * sn;
;             }
;           }
;         }
	v_and_b32_e32 v0, 0x7c0, v125
	v_lshl_add_u64 v[138:139], v[70:71], 0, v[0:1]
	v_lshl_add_u64 v[140:141], v[72:73], 0, v[0:1]
	global_load_dwordx4 v[126:129], v[138:139], off
	global_load_dwordx4 v[134:137], v[140:141], off
	global_load_dwordx4 v[216:219], v[138:139], off offset:32
	global_load_dwordx4 v[220:223], v[140:141], off offset:32
	v_lshlrev_b32_e32 v0, 6, v125
	v_and_b32_e32 v0, 0xfc0, v0
	v_lshl_add_u64 v[138:139], v[74:75], 0, v[0:1]
	v_lshl_add_u64 v[140:141], v[76:77], 0, v[0:1]
	global_load_dwordx4 v[224:227], v[138:139], off
	global_load_dwordx4 v[228:231], v[140:141], off
	global_load_dwordx4 v[232:235], v[138:139], off offset:32
	global_load_dwordx4 v[236:239], v[140:141], off offset:32
	s_waitcnt vmcnt(6)
	v_pk_mul_f32 v[142:143], v[88:89], v[134:135]
	v_pk_mul_f32 v[134:135], v[84:85], v[134:135]
	v_pk_fma_f32 v[84:85], v[84:85], v[126:127], v[142:143]
	v_pk_fma_f32 v[88:89], v[88:89], v[126:127], v[134:135] neg_lo:[0,0,1] neg_hi:[0,0,1]
	v_pk_mul_f32 v[126:127], v[90:91], v[136:137]
	v_pk_mul_f32 v[134:135], v[86:87], v[136:137]
	v_pk_fma_f32 v[86:87], v[86:87], v[128:129], v[126:127]
	v_pk_fma_f32 v[90:91], v[90:91], v[128:129], v[134:135] neg_lo:[0,0,1] neg_hi:[0,0,1]
	s_waitcnt vmcnt(4)
	v_pk_mul_f32 v[142:143], v[96:97], v[220:221]
	v_pk_mul_f32 v[220:221], v[92:93], v[220:221]
	v_pk_fma_f32 v[92:93], v[92:93], v[216:217], v[142:143]
	v_pk_fma_f32 v[96:97], v[96:97], v[216:217], v[220:221] neg_lo:[0,0,1] neg_hi:[0,0,1]
	v_pk_mul_f32 v[216:217], v[98:99], v[222:223]
	v_pk_mul_f32 v[220:221], v[94:95], v[222:223]
	v_pk_fma_f32 v[94:95], v[94:95], v[218:219], v[216:217]
	v_pk_fma_f32 v[98:99], v[98:99], v[218:219], v[220:221] neg_lo:[0,0,1] neg_hi:[0,0,1]
	s_waitcnt vmcnt(2)
	v_pk_mul_f32 v[142:143], v[104:105], v[228:229]
	v_pk_mul_f32 v[228:229], v[100:101], v[228:229]
	v_pk_fma_f32 v[100:101], v[100:101], v[224:225], v[142:143]
	v_pk_fma_f32 v[104:105], v[104:105], v[224:225], v[228:229] neg_lo:[0,0,1] neg_hi:[0,0,1]
	v_pk_mul_f32 v[224:225], v[106:107], v[230:231]
	v_pk_mul_f32 v[228:229], v[102:103], v[230:231]
	v_pk_fma_f32 v[102:103], v[102:103], v[226:227], v[224:225]
	v_pk_fma_f32 v[106:107], v[106:107], v[226:227], v[228:229] neg_lo:[0,0,1] neg_hi:[0,0,1]
	s_waitcnt vmcnt(0)
	v_pk_mul_f32 v[142:143], v[110:111], v[236:237]
	v_pk_mul_f32 v[236:237], v[108:109], v[236:237]
	v_pk_fma_f32 v[108:109], v[108:109], v[232:233], v[142:143]
	v_pk_fma_f32 v[110:111], v[110:111], v[232:233], v[236:237] neg_lo:[0,0,1] neg_hi:[0,0,1]
	v_pk_mul_f32 v[232:233], v[114:115], v[238:239]
	v_pk_mul_f32 v[236:237], v[112:113], v[238:239]
	v_pk_fma_f32 v[112:113], v[112:113], v[234:235], v[232:233]
	v_pk_fma_f32 v[114:115], v[114:115], v[234:235], v[236:237] neg_lo:[0,0,1] neg_hi:[0,0,1]

; DI int crow(int reg, int h) { return (reg & 3) + 8 * (reg >> 2) + 4 * h; }
; DI void phase_in(const Params& p, char* wsb, int layer, char* lds) {
;     ...
;         const float* gain = (na ? (kind == 0 ? p.na_qg : p.na_kg) : (kind == 0 ? p.swa_qg : p.swa_kg)) + layer * 64;
;         float ss = 0.f;
; #pragma unroll
;         for (int ai = 0; ai < 2; ++ai)
; #pragma unroll
;           for (int reg = 0; reg < 16; ++reg) ss += acc[ai][bi][reg] * acc[ai][bi][reg];
;         ss += __shfl_xor(ss, 32);
;         const float rn = rsqrtf(ss * (1.f / 64.f) + 1e-6f);
;         float v[2][16];
; #pragma unroll
;         for (int ai = 0; ai < 2; ++ai)
; #pragma unroll
;           for (int reg = 0; reg < 16; ++reg) v[ai][reg] = acc[ai][bi][reg] * rn * gain[ai * 32 + crow(reg, h)];
.LBB0_621:
	v_cndmask_b32_e64 v0, v200, v201, s[8:9]
	v_cndmask_b32_e64 v82, v202, v203, s[8:9]
	v_cndmask_b32_e64 v0, v82, v0, s[6:7]
	v_readlane_b32 s6, v244, 0
	v_readlane_b32 s7, v244, 1
	v_pk_mul_f32 v[92:93], v[8:9], v[8:9]
	v_pk_mul_f32 v[90:91], v[10:11], v[10:11]
	v_lshl_add_u64 v[82:83], s[6:7], 0, v[0:1]
	global_load_dwordx2 v[82:83], v[82:83], off
	v_mul_f32_e32 v0, v19, v19
	v_fmac_f32_e32 v0, v18, v18
	v_fmac_f32_e32 v0, v20, v20
	v_fmac_f32_e32 v0, v21, v21
	v_fmac_f32_e32 v0, v22, v22
	v_fmac_f32_e32 v0, v23, v23
	v_fmac_f32_e32 v0, v24, v24
	v_fmac_f32_e32 v0, v25, v25
	v_fmac_f32_e32 v0, v26, v26
	v_fmac_f32_e32 v0, v27, v27
	v_fmac_f32_e32 v0, v28, v28
	v_fmac_f32_e32 v0, v29, v29
	v_fmac_f32_e32 v0, v30, v30
	v_fmac_f32_e32 v0, v31, v31
	v_fmac_f32_e32 v0, v32, v32
	v_fmac_f32_e32 v0, v33, v33
	v_fmac_f32_e32 v0, v2, v2
	v_fmac_f32_e32 v0, v3, v3
	v_fmac_f32_e32 v0, v4, v4
	v_fmac_f32_e32 v0, v5, v5
	v_fmac_f32_e32 v0, v6, v6
	v_fmac_f32_e32 v0, v7, v7
	v_add_f32_e32 v0, v92, v0
	v_add_f32_e32 v0, v93, v0
	v_add_f32_e32 v0, v90, v0
	v_pk_mul_f32 v[88:89], v[12:13], v[12:13]
	v_add_f32_e32 v0, v91, v0
	v_add_f32_e32 v0, v88, v0
	v_pk_mul_f32 v[86:87], v[14:15], v[14:15]
	v_add_f32_e32 v0, v89, v0
	v_add_f32_e32 v0, v86, v0
	v_pk_mul_f32 v[84:85], v[16:17], v[16:17]
	v_add_f32_e32 v0, v87, v0
	v_cmp_lt_i32_e32 vcc, v187, v186
	v_add_f32_e32 v0, v84, v0
	v_add_f32_e32 v0, v85, v0
	v_cndmask_b32_e32 v84, v185, v187, vcc
	v_lshlrev_b32_e32 v84, 2, v84
	ds_bpermute_b32 v84, v84, v0
	s_waitcnt lgkmcnt(0)
	v_add_f32_e32 v0, v0, v84
	v_fmamk_f32 v0, v0, 0x3c800000, v179
	v_cmp_gt_f32_e32 vcc, s66, v0
	v_mul_f32_e32 v84, 0x4b800000, v0
	s_waitcnt vmcnt(0)
	v_lshl_add_u64 v[82:83], s[18:19], 2, v[82:83]
	v_cndmask_b32_e32 v0, v0, v84, vcc
	v_rsq_f32_e32 v0, v0
	s_nop 0
	v_mul_f32_e32 v84, 0x45800000, v0
	v_cndmask_b32_e32 v110, v0, v84, vcc
	v_lshlrev_b32_e32 v0, 2, v66
	v_lshl_add_u64 v[112:113], v[82:83], 0, v[0:1]
	global_load_dwordx4 v[82:85], v[112:113], off
	global_load_dwordx4 v[88:91], v[112:113], off offset:64
	global_load_dwordx4 v[246:249], v[112:113], off offset:32
	global_load_dwordx4 v[250:253], v[112:113], off offset:128
	v_pk_mul_f32 v[86:87], v[18:19], v[110:111] op_sel_hi:[1,0]
	v_pk_mul_f32 v[94:95], v[22:23], v[110:111] op_sel_hi:[1,0]
	global_load_dwordx4 v[104:107], v[112:113], off offset:192
	global_load_dwordx4 v[134:137], v[112:113], off offset:224
	v_pk_mul_f32 v[102:103], v[2:3], v[110:111] op_sel_hi:[1,0]
	global_load_dwordx4 v[96:99], v[112:113], off offset:96
	global_load_dwordx4 v[124:127], v[112:113], off offset:160
	s_waitcnt vmcnt(5)
	v_pk_mul_f32 v[86:87], v[82:83], v[86:87]
	v_pk_mul_f32 v[82:83], v[26:27], v[110:111] op_sel_hi:[1,0]
	s_waitcnt vmcnt(4)
	v_pk_mul_f32 v[82:83], v[88:89], v[82:83]
	v_pk_mul_f32 v[88:89], v[20:21], v[110:111] op_sel_hi:[1,0]
	s_nop 0
	v_pk_mul_f32 v[88:89], v[84:85], v[88:89]
	v_pk_mul_f32 v[84:85], v[28:29], v[110:111] op_sel_hi:[1,0]
	s_nop 0
	v_pk_mul_f32 v[84:85], v[84:85], v[90:91]
	s_waitcnt vmcnt(0)
	v_pk_mul_f32 v[94:95], v[246:247], v[94:95]
	v_pk_mul_f32 v[90:91], v[30:31], v[110:111] op_sel_hi:[1,0]
	s_nop 0
	v_pk_mul_f32 v[90:91], v[90:91], v[96:97]
	v_pk_mul_f32 v[96:97], v[24:25], v[110:111] op_sel_hi:[1,0]
	s_nop 0
	v_pk_mul_f32 v[96:97], v[248:249], v[96:97]
	v_pk_mul_f32 v[92:93], v[32:33], v[110:111] op_sel_hi:[1,0]
	s_nop 0
	v_pk_mul_f32 v[92:93], v[92:93], v[98:99]
	v_pk_mul_f32 v[112:113], v[8:9], v[110:111] op_sel_hi:[1,0]
	s_waitcnt vmcnt(0)
	v_pk_mul_f32 v[102:103], v[102:103], v[250:251]
	v_pk_mul_f32 v[98:99], v[10:11], v[110:111] op_sel_hi:[1,0]
	v_pk_mul_f32 v[112:113], v[112:113], v[126:127]
	v_pk_mul_f32 v[98:99], v[98:99], v[104:105]
	v_pk_mul_f32 v[104:105], v[4:5], v[110:111] op_sel_hi:[1,0]
	s_nop 0
	v_pk_mul_f32 v[104:105], v[104:105], v[252:253]
	v_pk_mul_f32 v[100:101], v[12:13], v[110:111] op_sel_hi:[1,0]
	s_nop 0
	v_pk_mul_f32 v[100:101], v[100:101], v[106:107]
	v_pk_mul_f32 v[106:107], v[6:7], v[110:111] op_sel_hi:[1,0]
	s_nop 0
	v_pk_mul_f32 v[108:109], v[106:107], v[124:125]
	v_pk_mul_f32 v[106:107], v[14:15], v[110:111] op_sel_hi:[1,0]
	v_pk_mul_f32 v[110:111], v[16:17], v[110:111] op_sel_hi:[1,0]
	v_pk_mul_f32 v[106:107], v[106:107], v[134:135]
	v_pk_mul_f32 v[110:111], v[110:111], v[136:137]
	s_and_saveexec_b64 s[6:7], s[54:55]
	s_cbranch_execz .LBB0_623
; DI int crow(int reg, int h) { return (reg & 3) + 8 * (reg >> 2) + 4 * h; }
; DI void phase_in(const Params& p, char* wsb, int layer, char* lds) {
;     ...
;         if (!na && !isctx) {
;           const int prow = pos >> 6, pcol = pos & 63;
; #pragma unroll
;           for (int ai = 0; ai < 2; ++ai) {
;             const float* ct = ai == 0 ? rope + prow * 16 : rope + 1024 + pcol * 16;
;             const float* st = ai == 0 ? rope + 512 + prow * 16 : rope + 2048 + pcol * 16;
; #pragma unroll
;             for (int reg = 0; reg < 8; ++reg) {
;               int j = crow(reg, h);
;               float cs = ct[j], sn = st[j];
;               float x1 = v[ai][reg], x2 = v[ai][reg + 8];
;               v[ai][reg] = x1 * cs - x2 * sn;
;               v[ai][reg + 8] = x2 * cs + x1 * sn;
;             }
;           }
;         }
	v_and_b32_e32 v0, 0x7c0, v114
	v_lshl_add_u64 v[138:139], v[70:71], 0, v[0:1]
	v_lshl_add_u64 v[140:141], v[72:73], 0, v[0:1]
	global_load_dwordx4 v[126:129], v[138:139], off
	global_load_dwordx4 v[134:137], v[140:141], off
	global_load_dwordx4 v[216:219], v[138:139], off offset:32
	global_load_dwordx4 v[220:223], v[140:141], off offset:32
	v_lshlrev_b32_e32 v0, 6, v114
	v_and_b32_e32 v0, 0xfc0, v0
	v_lshl_add_u64 v[138:139], v[74:75], 0, v[0:1]
	v_lshl_add_u64 v[140:141], v[76:77], 0, v[0:1]
	global_load_dwordx4 v[224:227], v[138:139], off
	global_load_dwordx4 v[228:231], v[140:141], off
	global_load_dwordx4 v[232:235], v[138:139], off offset:32
	global_load_dwordx4 v[236:239], v[140:141], off offset:32
	s_waitcnt vmcnt(6)
	v_pk_mul_f32 v[142:143], v[86:87], v[134:135]
	v_pk_mul_f32 v[134:135], v[82:83], v[134:135]
	v_pk_fma_f32 v[82:83], v[82:83], v[126:127], v[142:143]
	v_pk_fma_f32 v[86:87], v[86:87], v[126:127], v[134:135] neg_lo:[0,0,1] neg_hi:[0,0,1]
	v_pk_mul_f32 v[126:127], v[88:89], v[136:137]
	v_pk_mul_f32 v[134:135], v[84:85], v[136:137]
	v_pk_fma_f32 v[84:85], v[84:85], v[128:129], v[126:127]
	v_pk_fma_f32 v[88:89], v[88:89], v[128:129], v[134:135] neg_lo:[0,0,1] neg_hi:[0,0,1]
	s_waitcnt vmcnt(4)
	v_pk_mul_f32 v[142:143], v[94:95], v[220:221]
	v_pk_mul_f32 v[220:221], v[90:91], v[220:221]
	v_pk_fma_f32 v[90:91], v[90:91], v[216:217], v[142:143]
	v_pk_fma_f32 v[94:95], v[94:95], v[216:217], v[220:221] neg_lo:[0,0,1] neg_hi:[0,0,1]
	v_pk_mul_f32 v[216:217], v[96:97], v[222:223]
	v_pk_mul_f32 v[220:221], v[92:93], v[222:223]
	v_pk_fma_f32 v[92:93], v[92:93], v[218:219], v[216:217]
	v_pk_fma_f32 v[96:97], v[96:97], v[218:219], v[220:221] neg_lo:[0,0,1] neg_hi:[0,0,1]
	s_waitcnt vmcnt(2)
	v_pk_mul_f32 v[142:143], v[102:103], v[228:229]
	v_pk_mul_f32 v[228:229], v[98:99], v[228:229]
	v_pk_fma_f32 v[98:99], v[98:99], v[224:225], v[142:143]
	v_pk_fma_f32 v[102:103], v[102:103], v[224:225], v[228:229] neg_lo:[0,0,1] neg_hi:[0,0,1]
	v_pk_mul_f32 v[224:225], v[104:105], v[230:231]
	v_pk_mul_f32 v[228:229], v[100:101], v[230:231]
	v_pk_fma_f32 v[100:101], v[100:101], v[226:227], v[224:225]
	v_pk_fma_f32 v[104:105], v[104:105], v[226:227], v[228:229] neg_lo:[0,0,1] neg_hi:[0,0,1]
	s_waitcnt vmcnt(0)
	v_pk_mul_f32 v[142:143], v[108:109], v[236:237]
	v_pk_mul_f32 v[236:237], v[106:107], v[236:237]
	v_pk_fma_f32 v[106:107], v[106:107], v[232:233], v[142:143]
	v_pk_fma_f32 v[108:109], v[108:109], v[232:233], v[236:237] neg_lo:[0,0,1] neg_hi:[0,0,1]
	v_pk_mul_f32 v[232:233], v[112:113], v[238:239]
	v_pk_mul_f32 v[236:237], v[110:111], v[238:239]
	v_pk_fma_f32 v[110:111], v[110:111], v[234:235], v[232:233]
	v_pk_fma_f32 v[112:113], v[112:113], v[234:235], v[236:237] neg_lo:[0,0,1] neg_hi:[0,0,1]
